# exact tile skip uses the workgroup's smallest actual running max (valid rows) instead of the -|q||k| lower bound, margins 153 / 1.02
# speedup vs baseline: 1.0161x; 1.0161x over previous
; #define LDS_AS __attribute__((address_space(3)))
; template <int MODE>
; DI void prompt_unit(const Params& p, int b, int h, int qt, char* smem) {
;     ...
;         if (kt > 0) pload(kt - 1);
;         if (!wdone) {
;             LDS_AS const char* sb = lb + stg * PSTG;
;             if (MODE == 1 && kt * 64 + 63 < wq0) attn_tile64_fox(sb, sb + 9216, sb + 18432, q, st, lane);
.Lfoxp_entry:
	s_cmp_eq_u32 s100, -2
	s_cbranch_scc1 .LBB0_548
	s_mul_i32 s38, s98, 0x4900
	s_addk_i32 s38, 0x100
	s_mov_b32 s39, 0x9300
	s_xor_b32 s46, s98, 1
	s_mul_i32 s46, s46, 0x4900
	s_addk_i32 s46, 0x100
	s_add_i32 s10, s100, 1
	s_mov_b32 s42, 0
	s_cmp_lt_u32 s100, 22
	s_cbranch_scc1 .Lfsk_none
	v_cmp_gt_i32_e32 vcc, s88, v88
	v_mov_b32_e32 v164, 0x7f800000
	s_nop 0
	v_cndmask_b32_e32 v164, v164, v94, vcc
	v_xor_b32_e32 v165, 1, v174
	v_lshlrev_b32_e32 v165, 2, v165
	ds_bpermute_b32 v244, v165, v164
	s_waitcnt lgkmcnt(0)
	v_min_f32_e32 v164, v164, v244
	v_xor_b32_e32 v165, 2, v174
	v_lshlrev_b32_e32 v165, 2, v165
	ds_bpermute_b32 v244, v165, v164
	s_waitcnt lgkmcnt(0)
	v_min_f32_e32 v164, v164, v244
	v_xor_b32_e32 v165, 4, v174
	v_lshlrev_b32_e32 v165, 2, v165
	ds_bpermute_b32 v244, v165, v164
	s_waitcnt lgkmcnt(0)
	v_min_f32_e32 v164, v164, v244
	v_xor_b32_e32 v165, 8, v174
	v_lshlrev_b32_e32 v165, 2, v165
	ds_bpermute_b32 v244, v165, v164
	s_waitcnt lgkmcnt(0)
	v_min_f32_e32 v164, v164, v244
	v_xor_b32_e32 v165, 16, v174
	v_lshlrev_b32_e32 v165, 2, v165
	ds_bpermute_b32 v244, v165, v164
	s_waitcnt lgkmcnt(0)
	v_min_f32_e32 v164, v164, v244
	v_lshrrev_b32_e32 v165, 6, v138
	v_lshlrev_b32_e32 v165, 2, v165
	v_add_u32_e32 v165, 0x1f000, v165
	ds_write_b32 v165, v164
	s_waitcnt lgkmcnt(0)
	s_barrier
	v_mov_b32_e32 v165, 0x1f000
	ds_read_b128 v[132:135], v165
	ds_read_b128 v[160:163], v165 offset:16
	v_mul_f32_e32 v136, v249, v250
	v_sqrt_f32_e32 v136, v136
	s_waitcnt lgkmcnt(0)
	v_min3_f32 v164, v132, v133, v134
	v_min3_f32 v164, v164, v135, v160
	v_min3_f32 v164, v164, v161, v162
	v_min_f32_e32 v164, v164, v163
	v_mul_f32_e32 v136, 0x3ebc5bb7, v136
	v_add_f32_e32 v136, v136, v95
	v_add_f32_e32 v136, 0x43190000, v136
	v_sub_f32_e32 v136, v136, v164
	v_cmp_gt_f32_e32 vcc, v251, v136
	s_not_b64 s[42:43], vcc
	s_ff1_i32_b64 s42, s[42:43]
	s_cmp_lt_i32 s42, 0
	s_cselect_b32 s42, 64, s42
	s_min_i32 s42, s42, s100
	s_and_b32 s42, s42, -2
.Lfsk_none:
	s_sub_i32 s10, s10, s42
	s_lshl_b32 s43, s42, 8
	s_add_u32 s30, s30, s43
	s_addc_u32 s31, s31, 0
	s_mov_b32 s43, 0
	s_lshl_b64 s[42:43], s[42:43], 19
	v_lshl_add_u64 v[92:93], v[92:93], 0, s[42:43]
	s_mov_b32 s35, 0
	s_mov_b32 s37, 0
	v_add_u32_e32 v157, v104, v101
	v_add_u32_e32 v158, v105, v103
	v_add_u32_e32 v159, v98, v90
	v_xor_b32_e32 v112, 32, v174
	v_lshlrev_b32_e32 v112, 2, v112
	v_mov_b32_e32 v108, v107
	v_mov_b32_e32 v109, 0
	v_mov_b32_e32 v110, 0
	v_mov_b32_e32 v111, 0
	s_and_b64 vcc, exec, s[4:5]
	s_cbranch_vccz .Lfoxp_loop
	v_add_u32_e32 v97, s38, v104
	v_add_u32_e32 v100, s38, v157
	ds_read_b128 v[48:51], v97 offset:18560
	ds_read_b128 v[52:55], v97 offset:18592
	ds_read_b128 v[56:59], v97 offset:18624
	ds_read_b128 v[60:63], v97 offset:18656
	ds_read_b128 v[208:211], v100 offset:4608
	ds_read_b128 v[212:215], v100 offset:4640
	ds_read_b128 v[216:219], v100 offset:4672
	ds_read_b128 v[220:223], v100 offset:4704
	ds_read_b128 v[32:35], v97 offset:18432
	ds_read_b128 v[36:39], v97 offset:18464
	ds_read_b128 v[40:43], v97 offset:18496
	ds_read_b128 v[44:47], v97 offset:18528
	ds_read_b128 v[224:227], v100 offset:0
	ds_read_b128 v[228:231], v100 offset:32
	ds_read_b128 v[232:235], v100 offset:64
	ds_read_b128 v[236:239], v100 offset:96
	s_waitcnt lgkmcnt(11)
	v_mfma_f32_32x32x16_bf16 v[48:63], v[208:211], v[72:75], v[48:63]
	s_waitcnt lgkmcnt(10)
	v_mfma_f32_32x32x16_bf16 v[48:63], v[212:215], v[64:67], v[48:63]
	s_waitcnt lgkmcnt(9)
	v_mfma_f32_32x32x16_bf16 v[48:63], v[216:219], v[68:71], v[48:63]
	s_waitcnt lgkmcnt(8)
	v_mfma_f32_32x32x16_bf16 v[48:63], v[220:223], v[76:79], v[48:63]
	s_waitcnt lgkmcnt(3)
	v_mfma_f32_32x32x16_bf16 v[32:47], v[224:227], v[72:75], v[32:47]
	s_waitcnt lgkmcnt(2)
	v_mfma_f32_32x32x16_bf16 v[32:47], v[228:231], v[64:67], v[32:47]
	s_waitcnt lgkmcnt(1)
	v_mfma_f32_32x32x16_bf16 v[32:47], v[232:235], v[68:71], v[32:47]
	s_waitcnt lgkmcnt(0)
	v_mfma_f32_32x32x16_bf16 v[32:47], v[236:239], v[76:79], v[32:47]
	s_nop 7
	s_nop 7
